# GLA output unit: cache-warming loads for value slices 1 and 2 (state rows and V rows) issued next to slice 0's loads
# speedup vs baseline: 1.0005x; 1.0005x over previous
.LBB0_4809:
	s_or_b64 exec, exec, s[0:1]
	v_mul_lo_u32 v24, v79, s59
	v_lshlrev_b32_e32 v25, 2, v48
	v_add3_u32 v28, 0, v24, v25
	s_waitcnt lgkmcnt(0)
	s_barrier
	ds_read_b32 v24, v28
	s_movk_i32 s0, 0x2ff
	v_cmp_lt_i32_e32 vcc, s0, v54
	v_mov_b32_e32 v25, 0
	v_lshl_add_u32 v27, v48, 2, 0
	v_mov_b32_e32 v26, 0
	s_and_saveexec_b64 s[0:1], vcc
	ds_read_b32 v26, v27 offset:53248
	s_or_b64 exec, exec, s[0:1]
	s_waitcnt vmcnt(16)
	ds_read_b32 v29, v28 offset:4
	s_and_saveexec_b64 s[0:1], vcc
	ds_read_b32 v25, v27 offset:53252
	s_or_b64 exec, exec, s[0:1]
	s_waitcnt vmcnt(10)
	ds_read_b32 v30, v28 offset:8
	s_waitcnt vmcnt(8)
	v_mov_b32_e32 v32, 0
	v_mov_b32_e32 v31, 0
	s_and_saveexec_b64 s[0:1], vcc
	ds_read_b32 v31, v27 offset:53256
	s_or_b64 exec, exec, s[0:1]
	s_waitcnt vmcnt(7)
	ds_read_b32 v33, v28 offset:12
	s_and_saveexec_b64 s[0:1], vcc
	ds_read_b32 v32, v27 offset:53260
	s_or_b64 exec, exec, s[0:1]
	s_waitcnt vmcnt(6)
	ds_read_b32 v34, v28 offset:16
	s_waitcnt vmcnt(4)
	v_mov_b32_e32 v36, 0
	v_mov_b32_e32 v35, 0
	s_and_saveexec_b64 s[0:1], vcc
	ds_read_b32 v35, v27 offset:53264
	s_or_b64 exec, exec, s[0:1]
	s_waitcnt vmcnt(3)
	ds_read_b32 v37, v28 offset:20
	s_and_saveexec_b64 s[0:1], vcc
	ds_read_b32 v36, v27 offset:53268
	s_or_b64 exec, exec, s[0:1]
	s_waitcnt vmcnt(1)
	ds_read_b32 v39, v28 offset:24
	v_mov_b32_e32 v38, 0
	s_waitcnt vmcnt(0)
	v_mov_b32_e32 v40, 0
	s_and_saveexec_b64 s[0:1], vcc
	ds_read_b32 v40, v27 offset:53272
	s_or_b64 exec, exec, s[0:1]
	ds_read_b32 v28, v28 offset:28
	s_and_saveexec_b64 s[0:1], vcc
	ds_read_b32 v38, v27 offset:53276
	s_or_b64 exec, exec, s[0:1]
	s_waitcnt lgkmcnt(6)
	v_add_f32_e32 v25, v29, v25
	v_add_f32_e32 v24, v24, v26
	v_mul_f32_e32 v24, 0x3fb8aa3b, v24
	v_mul_f32_e32 v25, 0x3fb8aa3b, v25
	v_exp_f32_e32 v24, v24
	v_exp_f32_e32 v25, v25
	s_waitcnt lgkmcnt(0)
	v_add_f32_e32 v26, v28, v38
	v_lshlrev_b32_e32 v28, 16, v20
	v_and_b32_e32 v20, 0xffff0000, v20
	v_mul_f32_e32 v28, 0x3d93cd3a, v28
	v_mul_f32_e32 v20, 0x3d93cd3a, v20
	v_mul_f32_e32 v28, v28, v24
	v_mul_f32_e32 v20, v20, v25
	v_rcp_f32_e32 v24, v24
	v_rcp_f32_e32 v25, v25
	v_cvt_pk_bf16_f32 v20, v28, v20
	v_lshlrev_b32_e32 v28, 16, v16
	v_and_b32_e32 v16, 0xffff0000, v16
	v_add_f32_e32 v32, v33, v32
	v_add_f32_e32 v30, v30, v31
	v_mul_f32_e32 v24, v24, v28
	v_mul_f32_e32 v16, v25, v16
	v_cvt_pk_bf16_f32 v16, v24, v16
	v_mul_f32_e32 v24, 0x3fb8aa3b, v30
	v_mul_f32_e32 v25, 0x3fb8aa3b, v32
	v_exp_f32_e32 v24, v24
	v_exp_f32_e32 v25, v25
	v_lshlrev_b32_e32 v28, 16, v21
	v_and_b32_e32 v21, 0xffff0000, v21
	v_mul_f32_e32 v28, 0x3d93cd3a, v28
	v_mul_f32_e32 v21, 0x3d93cd3a, v21
	v_mul_f32_e32 v28, v28, v24
	v_mul_f32_e32 v21, v21, v25
	v_rcp_f32_e32 v24, v24
	v_rcp_f32_e32 v25, v25
	v_cvt_pk_bf16_f32 v21, v28, v21
	v_lshlrev_b32_e32 v28, 16, v17
	v_and_b32_e32 v17, 0xffff0000, v17
	v_add_f32_e32 v36, v37, v36
	v_add_f32_e32 v34, v34, v35
	v_mul_f32_e32 v24, v24, v28
	v_mul_f32_e32 v17, v25, v17
	v_cvt_pk_bf16_f32 v17, v24, v17
	v_mul_f32_e32 v24, 0x3fb8aa3b, v34
	v_mul_f32_e32 v25, 0x3fb8aa3b, v36
	v_exp_f32_e32 v24, v24
	v_exp_f32_e32 v25, v25
	v_lshlrev_b32_e32 v28, 16, v22
	v_and_b32_e32 v22, 0xffff0000, v22
	v_mul_f32_e32 v28, 0x3d93cd3a, v28
	v_mul_f32_e32 v22, 0x3d93cd3a, v22
	v_mul_f32_e32 v28, v28, v24
	v_mul_f32_e32 v22, v22, v25
	v_rcp_f32_e32 v24, v24
	v_rcp_f32_e32 v25, v25
	v_cvt_pk_bf16_f32 v22, v28, v22
	v_lshlrev_b32_e32 v28, 16, v18
	v_and_b32_e32 v18, 0xffff0000, v18
	v_add_f32_e32 v27, v39, v40
	v_mul_f32_e32 v24, v24, v28
	v_mul_f32_e32 v18, v25, v18
	v_cvt_pk_bf16_f32 v18, v24, v18
	v_mul_f32_e32 v24, 0x3fb8aa3b, v27
	v_mul_f32_e32 v25, 0x3fb8aa3b, v26
	v_exp_f32_e32 v24, v24
	v_exp_f32_e32 v25, v25
	v_lshlrev_b32_e32 v26, 16, v23
	v_and_b32_e32 v23, 0xffff0000, v23
	v_mul_f32_e32 v26, 0x3d93cd3a, v26
	v_mul_f32_e32 v23, 0x3d93cd3a, v23
	v_mul_f32_e32 v26, v26, v24
	v_mul_f32_e32 v23, v23, v25
	v_rcp_f32_e32 v24, v24
	v_rcp_f32_e32 v25, v25
	v_cvt_pk_bf16_f32 v23, v26, v23
	v_lshlrev_b32_e32 v26, 16, v19
	v_and_b32_e32 v19, 0xffff0000, v19
	v_mul_f32_e32 v24, v24, v26
	v_mul_f32_e32 v19, v25, v19
	v_cvt_pk_bf16_f32 v19, v24, v19
	v_mul_lo_u32 v24, v79, s60
	v_lshlrev_b32_e32 v25, 1, v48
	v_add3_u32 v58, 0, v24, v25
	ds_write_b128 v58, v[20:23] offset:54272
	v_add3_u32 v20, s61, v24, v25
	ds_write_b128 v20, v[16:19]
	v_mul_lo_u32 v16, v80, s59
	v_lshlrev_b32_e32 v17, 2, v50
	v_add3_u32 v20, 0, v16, v17
	ds_read_b32 v16, v20
	s_movk_i32 s0, 0xff
	v_cmp_lt_i32_e32 vcc, s0, v54
	v_mov_b32_e32 v17, 0
	v_lshl_add_u32 v19, v50, 2, 0
	v_mov_b32_e32 v18, 0
	s_and_saveexec_b64 s[0:1], vcc
	ds_read_b32 v18, v19 offset:53248
	s_or_b64 exec, exec, s[0:1]
	ds_read_b32 v21, v20 offset:4
	s_and_saveexec_b64 s[0:1], vcc
	ds_read_b32 v17, v19 offset:53252
	s_or_b64 exec, exec, s[0:1]
	ds_read_b32 v22, v20 offset:8
	v_mov_b32_e32 v24, 0
	v_mov_b32_e32 v23, 0
	s_and_saveexec_b64 s[0:1], vcc
	ds_read_b32 v23, v19 offset:53256
	s_or_b64 exec, exec, s[0:1]
	ds_read_b32 v25, v20 offset:12
	s_and_saveexec_b64 s[0:1], vcc
	ds_read_b32 v24, v19 offset:53260
	s_or_b64 exec, exec, s[0:1]
	ds_read_b32 v26, v20 offset:16
	v_mov_b32_e32 v28, 0
	v_mov_b32_e32 v27, 0
	s_and_saveexec_b64 s[0:1], vcc
	ds_read_b32 v27, v19 offset:53264
	s_or_b64 exec, exec, s[0:1]
	ds_read_b32 v29, v20 offset:20
	s_and_saveexec_b64 s[0:1], vcc
	ds_read_b32 v28, v19 offset:53268
	s_or_b64 exec, exec, s[0:1]
	ds_read_b32 v31, v20 offset:24
	v_mov_b32_e32 v30, 0
	v_mov_b32_e32 v32, 0
	s_and_saveexec_b64 s[0:1], vcc
	ds_read_b32 v32, v19 offset:53272
	s_or_b64 exec, exec, s[0:1]
	ds_read_b32 v20, v20 offset:28
	s_and_saveexec_b64 s[0:1], vcc
	ds_read_b32 v30, v19 offset:53276
	s_or_b64 exec, exec, s[0:1]
	s_waitcnt lgkmcnt(6)
	v_add_f32_e32 v17, v21, v17
	v_add_f32_e32 v16, v16, v18
	v_mul_f32_e32 v16, 0x3fb8aa3b, v16
	v_mul_f32_e32 v17, 0x3fb8aa3b, v17
	v_exp_f32_e32 v16, v16
	v_exp_f32_e32 v17, v17
	s_waitcnt lgkmcnt(0)
	v_add_f32_e32 v18, v20, v30
	v_lshlrev_b32_e32 v20, 16, v12
	v_and_b32_e32 v12, 0xffff0000, v12
	v_mul_f32_e32 v20, 0x3d93cd3a, v20
	v_mul_f32_e32 v12, 0x3d93cd3a, v12
	v_mul_f32_e32 v20, v20, v16
	v_mul_f32_e32 v12, v12, v17
	v_rcp_f32_e32 v16, v16
	v_rcp_f32_e32 v17, v17
	v_cvt_pk_bf16_f32 v12, v20, v12
	v_lshlrev_b32_e32 v20, 16, v8
	v_and_b32_e32 v8, 0xffff0000, v8
	v_add_f32_e32 v24, v25, v24
	v_add_f32_e32 v22, v22, v23
	v_mul_f32_e32 v16, v16, v20
	v_mul_f32_e32 v8, v17, v8
	v_cvt_pk_bf16_f32 v8, v16, v8
	v_mul_f32_e32 v16, 0x3fb8aa3b, v22
	v_mul_f32_e32 v17, 0x3fb8aa3b, v24
	v_exp_f32_e32 v16, v16
	v_exp_f32_e32 v17, v17
	v_lshlrev_b32_e32 v20, 16, v13
	v_and_b32_e32 v13, 0xffff0000, v13
	v_mul_f32_e32 v20, 0x3d93cd3a, v20
	v_mul_f32_e32 v13, 0x3d93cd3a, v13
	v_mul_f32_e32 v20, v20, v16
	v_mul_f32_e32 v13, v13, v17
	v_rcp_f32_e32 v16, v16
	v_rcp_f32_e32 v17, v17
	v_cvt_pk_bf16_f32 v13, v20, v13
	v_lshlrev_b32_e32 v20, 16, v9
	v_and_b32_e32 v9, 0xffff0000, v9
	v_add_f32_e32 v28, v29, v28
	v_add_f32_e32 v26, v26, v27
	v_mul_f32_e32 v16, v16, v20
	v_mul_f32_e32 v9, v17, v9
	v_cvt_pk_bf16_f32 v9, v16, v9
	v_mul_f32_e32 v16, 0x3fb8aa3b, v26
	v_mul_f32_e32 v17, 0x3fb8aa3b, v28
	v_exp_f32_e32 v16, v16
	v_exp_f32_e32 v17, v17
	v_lshlrev_b32_e32 v20, 16, v14
	v_and_b32_e32 v14, 0xffff0000, v14
	v_mul_f32_e32 v20, 0x3d93cd3a, v20
	v_mul_f32_e32 v14, 0x3d93cd3a, v14
	v_mul_f32_e32 v20, v20, v16
	v_mul_f32_e32 v14, v14, v17
	v_rcp_f32_e32 v16, v16
	v_rcp_f32_e32 v17, v17
	v_cvt_pk_bf16_f32 v14, v20, v14
	v_lshlrev_b32_e32 v20, 16, v10
	v_and_b32_e32 v10, 0xffff0000, v10
	v_add_f32_e32 v19, v31, v32
	v_mul_f32_e32 v16, v16, v20
	v_mul_f32_e32 v10, v17, v10
	v_cvt_pk_bf16_f32 v10, v16, v10
	v_mul_f32_e32 v16, 0x3fb8aa3b, v19
	v_mul_f32_e32 v17, 0x3fb8aa3b, v18
	v_exp_f32_e32 v16, v16
	v_exp_f32_e32 v17, v17
	v_lshlrev_b32_e32 v18, 16, v15
	v_and_b32_e32 v15, 0xffff0000, v15
	v_mul_f32_e32 v18, 0x3d93cd3a, v18
	v_mul_f32_e32 v15, 0x3d93cd3a, v15
	v_mul_f32_e32 v18, v18, v16
	v_mul_f32_e32 v15, v15, v17
	v_rcp_f32_e32 v16, v16
	v_rcp_f32_e32 v17, v17
	v_cvt_pk_bf16_f32 v15, v18, v15
	v_lshlrev_b32_e32 v18, 16, v11
	v_and_b32_e32 v11, 0xffff0000, v11
	v_mul_f32_e32 v16, v16, v18
	v_mul_f32_e32 v11, v17, v11
	v_cvt_pk_bf16_f32 v11, v16, v11
	v_mul_lo_u32 v16, v80, s60
	v_lshlrev_b32_e32 v17, 1, v50
	v_add3_u32 v84, 0, v16, v17
	ds_write_b128 v84, v[12:15] offset:54272
	v_add3_u32 v12, s61, v16, v17
	ds_write_b128 v12, v[8:11]
	v_mul_lo_u32 v8, v81, s59
	v_lshlrev_b32_e32 v9, 2, v52
	v_add3_u32 v12, 0, v8, v9
	ds_read_b32 v8, v12
	s_movk_i32 s0, 0xfeff
	v_cmp_lt_i32_e32 vcc, s0, v54
	v_mov_b32_e32 v9, 0
	v_lshl_add_u32 v11, v52, 2, 0
	v_mov_b32_e32 v10, 0
	s_and_saveexec_b64 s[0:1], vcc
	ds_read_b32 v10, v11 offset:53248
	s_or_b64 exec, exec, s[0:1]
	ds_read_b32 v13, v12 offset:4
	s_and_saveexec_b64 s[0:1], vcc
	ds_read_b32 v9, v11 offset:53252
	s_or_b64 exec, exec, s[0:1]
	ds_read_b32 v14, v12 offset:8
	v_mov_b32_e32 v16, 0
	v_mov_b32_e32 v15, 0
	s_and_saveexec_b64 s[0:1], vcc
	ds_read_b32 v15, v11 offset:53256
	s_or_b64 exec, exec, s[0:1]
	ds_read_b32 v17, v12 offset:12
	s_and_saveexec_b64 s[0:1], vcc
	ds_read_b32 v16, v11 offset:53260
	s_or_b64 exec, exec, s[0:1]
	ds_read_b32 v18, v12 offset:16
	v_mov_b32_e32 v20, 0
	v_mov_b32_e32 v19, 0
	s_and_saveexec_b64 s[0:1], vcc
	ds_read_b32 v19, v11 offset:53264
	s_or_b64 exec, exec, s[0:1]
	ds_read_b32 v21, v12 offset:20
	s_and_saveexec_b64 s[0:1], vcc
	ds_read_b32 v20, v11 offset:53268
	s_or_b64 exec, exec, s[0:1]
	ds_read_b32 v23, v12 offset:24
	v_mov_b32_e32 v22, 0
	v_mov_b32_e32 v24, 0
	s_and_saveexec_b64 s[0:1], vcc
	ds_read_b32 v24, v11 offset:53272
	s_or_b64 exec, exec, s[0:1]
	ds_read_b32 v12, v12 offset:28
	s_and_saveexec_b64 s[0:1], vcc
	ds_read_b32 v22, v11 offset:53276
	s_or_b64 exec, exec, s[0:1]
	s_waitcnt lgkmcnt(6)
	v_add_f32_e32 v9, v13, v9
	v_add_f32_e32 v8, v8, v10
	v_mul_f32_e32 v8, 0x3fb8aa3b, v8
	v_mul_f32_e32 v9, 0x3fb8aa3b, v9
	v_exp_f32_e32 v8, v8
	v_exp_f32_e32 v9, v9
	s_waitcnt lgkmcnt(0)
	v_add_f32_e32 v10, v12, v22
	v_lshlrev_b32_e32 v12, 16, v4
	v_and_b32_e32 v4, 0xffff0000, v4
	v_mul_f32_e32 v12, 0x3d93cd3a, v12
	v_mul_f32_e32 v4, 0x3d93cd3a, v4
	v_mul_f32_e32 v12, v12, v8
	v_mul_f32_e32 v4, v4, v9
	v_rcp_f32_e32 v8, v8
	v_rcp_f32_e32 v9, v9
	v_cvt_pk_bf16_f32 v4, v12, v4
	v_lshlrev_b32_e32 v12, 16, v0
	v_and_b32_e32 v0, 0xffff0000, v0
	v_add_f32_e32 v16, v17, v16
	v_add_f32_e32 v14, v14, v15
	v_mul_f32_e32 v8, v8, v12
	v_mul_f32_e32 v0, v9, v0
	v_cvt_pk_bf16_f32 v0, v8, v0
	v_mul_f32_e32 v8, 0x3fb8aa3b, v14
	v_mul_f32_e32 v9, 0x3fb8aa3b, v16
	v_exp_f32_e32 v8, v8
	v_exp_f32_e32 v9, v9
	v_lshlrev_b32_e32 v12, 16, v5
	v_and_b32_e32 v5, 0xffff0000, v5
	v_mul_f32_e32 v12, 0x3d93cd3a, v12
	v_mul_f32_e32 v5, 0x3d93cd3a, v5
	v_mul_f32_e32 v12, v12, v8
	v_mul_f32_e32 v5, v5, v9
	v_rcp_f32_e32 v8, v8
	v_rcp_f32_e32 v9, v9
	v_cvt_pk_bf16_f32 v5, v12, v5
	v_lshlrev_b32_e32 v12, 16, v1
	v_and_b32_e32 v1, 0xffff0000, v1
	v_add_f32_e32 v20, v21, v20
	v_add_f32_e32 v18, v18, v19
	v_mul_f32_e32 v8, v8, v12
	v_mul_f32_e32 v1, v9, v1
	v_cvt_pk_bf16_f32 v1, v8, v1
	v_mul_f32_e32 v8, 0x3fb8aa3b, v18
	v_mul_f32_e32 v9, 0x3fb8aa3b, v20
	v_exp_f32_e32 v8, v8
	v_exp_f32_e32 v9, v9
	v_lshlrev_b32_e32 v12, 16, v6
	v_and_b32_e32 v6, 0xffff0000, v6
	v_mul_f32_e32 v12, 0x3d93cd3a, v12
	v_mul_f32_e32 v6, 0x3d93cd3a, v6
	v_mul_f32_e32 v12, v12, v8
	v_mul_f32_e32 v6, v6, v9
	v_rcp_f32_e32 v8, v8
	v_rcp_f32_e32 v9, v9
	v_cvt_pk_bf16_f32 v6, v12, v6
	v_lshlrev_b32_e32 v12, 16, v2
	v_and_b32_e32 v2, 0xffff0000, v2
	v_add_f32_e32 v11, v23, v24
	v_mul_f32_e32 v8, v8, v12
	v_mul_f32_e32 v2, v9, v2
	v_cvt_pk_bf16_f32 v2, v8, v2
	v_mul_f32_e32 v8, 0x3fb8aa3b, v11
	v_mul_f32_e32 v9, 0x3fb8aa3b, v10
	v_exp_f32_e32 v8, v8
	v_exp_f32_e32 v9, v9
	v_lshlrev_b32_e32 v10, 16, v7
	v_and_b32_e32 v7, 0xffff0000, v7
	v_mul_f32_e32 v10, 0x3d93cd3a, v10
	v_mul_f32_e32 v7, 0x3d93cd3a, v7
	v_mul_f32_e32 v10, v10, v8
	v_mul_f32_e32 v7, v7, v9
	v_rcp_f32_e32 v8, v8
	v_rcp_f32_e32 v9, v9
	v_cvt_pk_bf16_f32 v7, v10, v7
	v_lshlrev_b32_e32 v10, 16, v3
	v_and_b32_e32 v3, 0xffff0000, v3
	s_lshl_b32 s0, s3, 2
	v_mul_f32_e32 v8, v8, v10
	v_mul_f32_e32 v3, v9, v3
	s_add_i32 s0, s0, s2
	v_cvt_pk_bf16_f32 v3, v8, v3
	v_mul_lo_u32 v8, v81, s60
	v_lshlrev_b32_e32 v9, 1, v52
	s_mul_hi_i32 s1, s0, 0x24000
	s_mul_i32 s0, s0, 0x24000
	v_add3_u32 v87, 0, v8, v9
	s_add_u32 s22, s46, s0
	ds_write_b128 v87, v[4:7] offset:54272
	v_add3_u32 v4, s61, v8, v9
	s_addc_u32 s23, s47, s1
	ds_write_b128 v4, v[0:3]
	v_mov_b64_e32 v[0:1], s[22:23]
	v_mad_i64_i32 v[2:3], s[0:1], v79, s54, v[0:1]
	v_mad_i64_i32 v[4:5], s[0:1], v80, s54, v[0:1]
	v_lshl_add_u64 v[2:3], v[48:49], 1, v[2:3]
	v_lshl_add_u64 v[4:5], v[50:51], 1, v[4:5]
	s_waitcnt lgkmcnt(0)
	s_barrier
	s_mov_b64 s[98:99], 0xc000
	s_mov_b64 s[100:101], 0x18000
	global_load_dwordx4 v[16:19], v[2:3], off
	v_lshl_add_u64 v[144:145], v[2:3], 0, s[98:99]
	global_load_dword v222, v[144:145], off
	v_lshl_add_u64 v[144:145], v[2:3], 0, s[100:101]
	global_load_dword v223, v[144:145], off
	global_load_dwordx4 v[20:23], v[4:5], off
	v_lshl_add_u64 v[144:145], v[4:5], 0, s[98:99]
	global_load_dword v224, v[144:145], off
	v_lshl_add_u64 v[144:145], v[4:5], 0, s[100:101]
	global_load_dword v225, v[144:145], off
	v_add_u32_e32 v4, 0x600, v54
	v_mul_hi_i32 v5, v4, s48
	v_lshrrev_b32_e32 v6, 31, v5
	v_ashrrev_i32_e32 v5, 2, v5
	v_add_u32_e32 v93, v5, v6
	v_mul_lo_u32 v5, v93, 24
	v_sub_u32_e32 v4, v4, v5
	v_mad_i64_i32 v[2:3], s[0:1], v81, s54, v[0:1]
	v_lshlrev_b32_e32 v64, 3, v4
	v_lshl_add_u64 v[2:3], v[52:53], 1, v[2:3]
	v_mad_i64_i32 v[4:5], s[0:1], v93, s54, v[0:1]
	v_ashrrev_i32_e32 v65, 31, v64
	v_lshl_add_u64 v[4:5], v[64:65], 1, v[4:5]
	global_load_dwordx4 v[28:31], v[2:3], off
	v_lshl_add_u64 v[144:145], v[2:3], 0, s[98:99]
	global_load_dword v226, v[144:145], off
	v_lshl_add_u64 v[144:145], v[2:3], 0, s[100:101]
	global_load_dword v227, v[144:145], off
	global_load_dwordx4 v[24:27], v[4:5], off
	v_lshl_add_u64 v[144:145], v[4:5], 0, s[98:99]
	global_load_dword v228, v[144:145], off
	v_lshl_add_u64 v[144:145], v[4:5], 0, s[100:101]
	global_load_dword v229, v[144:145], off
	v_add_u32_e32 v2, 0x800, v54
	v_mul_hi_i32 v3, v2, s48
	v_lshrrev_b32_e32 v4, 31, v3
	v_ashrrev_i32_e32 v3, 2, v3
	v_add_u32_e32 v94, v3, v4
	v_add_u32_e32 v4, 0xa00, v54
	v_mul_hi_i32 v5, v4, s48
	v_lshrrev_b32_e32 v6, 31, v5
	v_ashrrev_i32_e32 v5, 2, v5
	v_add_u32_e32 v95, v5, v6
	v_mul_lo_u32 v3, v94, 24
	v_mul_lo_u32 v5, v95, 24
	v_sub_u32_e32 v2, v2, v3
	v_sub_u32_e32 v4, v4, v5
	v_lshlrev_b32_e32 v66, 3, v2
	v_lshlrev_b32_e32 v68, 3, v4
	v_mad_i64_i32 v[2:3], s[0:1], v94, s54, v[0:1]
	v_ashrrev_i32_e32 v67, 31, v66
	v_mad_i64_i32 v[0:1], s[0:1], v95, s54, v[0:1]
	v_ashrrev_i32_e32 v69, 31, v68
	v_lshl_add_u64 v[2:3], v[66:67], 1, v[2:3]
	v_lshl_add_u64 v[0:1], v[68:69], 1, v[0:1]
	v_and_b32_e32 v99, 63, v78
	global_load_dwordx4 v[36:39], v[2:3], off
	v_lshl_add_u64 v[144:145], v[2:3], 0, s[98:99]
	global_load_dword v230, v[144:145], off
	v_lshl_add_u64 v[144:145], v[2:3], 0, s[100:101]
	global_load_dword v231, v[144:145], off
	global_load_dwordx4 v[32:35], v[0:1], off
	v_lshl_add_u64 v[144:145], v[0:1], 0, s[98:99]
	global_load_dword v232, v[144:145], off
	v_lshl_add_u64 v[144:145], v[0:1], 0, s[100:101]
	global_load_dword v233, v[144:145], off
	v_or_b32_e32 v2, s66, v99
	v_mov_b64_e32 v[0:1], s[36:37]
	v_mad_i64_i32 v[0:1], s[0:1], v2, s49, v[0:1]
	s_mul_i32 s0, s2, 0x180
	v_ashrrev_i32_e32 v2, 3, v54
	s_ashr_i32 s1, s0, 31
	v_and_b32_e32 v72, -8, v2
	v_ashrrev_i32_e32 v2, 3, v55
	v_lshl_add_u64 v[0:1], s[0:1], 1, v[0:1]
	v_ashrrev_i32_e32 v73, 31, v72
	v_and_b32_e32 v70, -8, v2
	v_lshl_add_u64 v[62:63], v[72:73], 1, v[0:1]
	v_ashrrev_i32_e32 v71, 31, v70
	v_lshl_add_u64 v[60:61], v[70:71], 1, v[0:1]
	global_load_dwordx4 v[44:47], v[62:63], off offset:3072
	global_load_dword v234, v[62:63], off offset:3328
	global_load_dword v235, v[62:63], off offset:3584
	global_load_dwordx4 v[40:43], v[60:61], off offset:3072
	global_load_dword v236, v[60:61], off offset:3328
	global_load_dword v237, v[60:61], off offset:3584
	v_ashrrev_i32_e32 v0, 6, v54
	v_and_b32_e32 v85, 1, v0
	v_ashrrev_i32_e32 v86, 7, v54
	v_and_b32_e32 v71, 31, v78
	v_cmp_lt_i32_e32 vcc, 3, v0
	v_lshlrev_b32_e32 v73, 5, v85
	v_lshlrev_b32_e32 v82, 5, v86
	s_and_saveexec_b64 s[2:3], vcc
	s_xor_b64 s[26:27], exec, s[2:3]
	v_lshlrev_b32_e32 v82, 5, v86
	v_lshlrev_b32_e32 v73, 5, v85
	v_or_b32_e32 v54, v82, v71
	s_or_saveexec_b64 s[26:27], s[26:27]
	v_bfe_u32 v83, v78, 5, 1
	s_xor_b64 exec, exec, s[26:27]
	s_cbranch_execz .LBB0_4865
	v_cmp_le_i32_e32 vcc, v86, v85
	s_and_saveexec_b64 s[2:3], vcc
	s_xor_b64 s[44:45], exec, s[2:3]
	s_cbranch_execz .LBB0_4862
	v_or_b32_e32 v0, v73, v71
	v_mul_u32_u24_e32 v0, 0x190, v0
	v_lshlrev_b32_e32 v4, 4, v83
	v_add3_u32 v55, 0, v0, v4
	v_lshlrev_b32_e32 v82, 5, v86
	ds_read_b128 v[0:3], v55 offset:54272
	v_or_b32_e32 v54, v82, v71
	v_mul_lo_u32 v5, v54, s60
	v_add3_u32 v92, s61, v5, v4
	ds_read_b128 v[4:7], v92
	ds_read_b128 v[88:91], v55 offset:54304
	ds_read_b128 v[100:103], v92 offset:32
	ds_read_b128 v[104:107], v55 offset:54336
	ds_read_b128 v[108:111], v92 offset:64
	ds_read_b128 v[194:197], v55 offset:54368
	ds_read_b128 v[198:201], v92 offset:96
	s_waitcnt lgkmcnt(6)
	v_mfma_f32_32x32x16_bf16 v[0:15], v[0:3], v[4:7], 0
	ds_read_b128 v[206:209], v55 offset:54400
	ds_read_b128 v[210:213], v92 offset:128
	s_waitcnt lgkmcnt(6)
	v_mfma_f32_32x32x16_bf16 v[0:15], v[88:91], v[100:103], v[0:15]
	ds_read_b128 v[88:91], v55 offset:54432
	ds_read_b128 v[100:103], v92 offset:160
	s_waitcnt lgkmcnt(6)
	v_mfma_f32_32x32x16_bf16 v[0:15], v[104:107], v[108:111], v[0:15]
	ds_read_b128 v[104:107], v55 offset:54464
	ds_read_b128 v[108:111], v92 offset:192
	s_waitcnt lgkmcnt(6)
	v_mfma_f32_32x32x16_bf16 v[0:15], v[194:197], v[198:201], v[0:15]
	ds_read_b128 v[194:197], v55 offset:54496
	ds_read_b128 v[198:201], v92 offset:224
	s_waitcnt lgkmcnt(6)
	v_mfma_f32_32x32x16_bf16 v[0:15], v[206:209], v[210:213], v[0:15]
	ds_read_b128 v[206:209], v55 offset:54528
	ds_read_b128 v[210:213], v92 offset:256
	s_waitcnt lgkmcnt(6)
	v_mfma_f32_32x32x16_bf16 v[0:15], v[88:91], v[100:103], v[0:15]
	ds_read_b128 v[88:91], v55 offset:54560
	ds_read_b128 v[100:103], v92 offset:288
	s_waitcnt lgkmcnt(6)
	v_mfma_f32_32x32x16_bf16 v[0:15], v[104:107], v[108:111], v[0:15]
	ds_read_b128 v[104:107], v55 offset:54592
	ds_read_b128 v[108:111], v92 offset:320
	s_waitcnt lgkmcnt(6)
	v_mfma_f32_32x32x16_bf16 v[0:15], v[194:197], v[198:201], v[0:15]
	ds_read_b128 v[194:197], v55 offset:54624
	ds_read_b128 v[198:201], v92 offset:352
	s_waitcnt lgkmcnt(6)
	v_mfma_f32_32x32x16_bf16 v[0:15], v[206:209], v[210:213], v[0:15]
	s_waitcnt lgkmcnt(4)
	v_mfma_f32_32x32x16_bf16 v[0:15], v[88:91], v[100:103], v[0:15]
	s_waitcnt lgkmcnt(2)
	v_mfma_f32_32x32x16_bf16 v[0:15], v[104:107], v[108:111], v[0:15]
	s_waitcnt lgkmcnt(0)
	v_mfma_f32_32x32x16_bf16 v[0:15], v[194:197], v[198:201], v[0:15]
